# compute waves raise their priority to 3 only during the forward-substitution chain (helpers stay at 3)
# baseline (speedup 1.0000x reference)
.Lmy_ck_nz:
	s_mov_b32 s100, 0xe000
	s_cmp_eq_u32 s23, 0
	s_cselect_b32 s100, 0x1c000, s100
	s_mov_b32 s101, 0x12e00
	s_cselect_b32 s101, 0x22100, s101
	s_lshl_b32 s96, s23, 13
	s_add_i32 s97, s96, 0x18000
	s_add_i32 s96, s96, 0xa000
	v_add_u32_e32 v225, s100, v1
	v_add_u32_e32 v236, s100, v0
	v_add_u32_e32 v34, s100, v10
	v_add_u32_e32 v226, s100, v2
	v_add_u32_e32 v227, s100, v3
	v_add_u32_e32 v228, s100, v4
	v_add_u32_e32 v229, s100, v5
	v_add_u32_e32 v237, s100, v6
	v_add_u32_e32 v238, s100, v7
	v_add_u32_e32 v230, s96, v8
	v_add_u32_e32 v239, s96, v9
	v_add_u32_e32 v231, s97, v8
	v_add_u32_e32 v26, s101, v1
	v_add_u32_e32 v27, s101, v0
	v_add_u32_e32 v35, s101, v10
	v_add_u32_e32 v28, s101, v2
	v_add_u32_e32 v29, s101, v3
	v_add_u32_e32 v30, s101, v4
	v_add_u32_e32 v31, s101, v5
	v_add_u32_e32 v32, s101, v6
	v_add_u32_e32 v33, s101, v7
	ds_read_b64 v[80:81], v237
	ds_read_b64 v[82:83], v238
	ds_read_b32 v36, v239
	ds_read_b32 v37, v239 offset:256
	ds_read_b128 v[88:91], v225
	ds_read_b128 v[92:95], v225 offset:1024
	ds_read_b128 v[96:99], v225 offset:2048
	ds_read_b128 v[100:103], v225 offset:3072
	ds_read_b32 v104, v227 offset:4
	ds_read_b32 v105, v227 offset:76
	ds_read_b64 v[106:107], v227 offset:8
	ds_read_b64 v[108:109], v227 offset:40
	ds_read_b32 v126, v229 offset:4
	ds_read_b32 v127, v229 offset:76
	ds_read_b64 v[128:129], v229 offset:8
	ds_read_b64 v[130:131], v229 offset:40
	ds_read_b64 v[110:111], v228
	ds_read_b64 v[112:113], v228 offset:32
	ds_read_b64 v[114:115], v228 offset:64
	ds_read_b64 v[116:117], v228 offset:96
	ds_read_b64 v[118:119], v228 offset:8
	ds_read_b64 v[120:121], v228 offset:40
	ds_read_b64 v[122:123], v228 offset:72
	ds_read_b64 v[124:125], v228 offset:104
	s_waitcnt lgkmcnt(15)
	v_mfma_f32_16x16x4_f32 v[240:243], v80, v36, 0
	v_mfma_f32_16x16x4_f32 v[240:243], v81, v37, v[240:243]
	v_mfma_f32_16x16x4_f32 v[240:243], v88, v208, v[240:243]
	ds_read_b64 v[186:187], v34
	ds_read_b64 v[190:191], v34 offset:1024
	v_mfma_f32_16x16x4_f32 v[244:247], v89, v209, 0
	ds_read_b64 v[194:195], v34 offset:2048
	ds_read_b64 v[198:199], v34 offset:3072
	v_mfma_f32_16x16x4_f32 v[240:243], v90, v210, v[240:243]
	ds_read_b64 v[184:185], v236
	ds_read_b64 v[188:189], v236 offset:1024
	ds_read_b64 v[132:133], v237 offset:9984
	v_mfma_f32_16x16x4_f32 v[244:247], v91, v211, v[244:247]
	ds_read_b64 v[134:135], v238 offset:9984
	ds_read_b64 v[192:193], v236 offset:2048
	ds_read_b64 v[196:197], v236 offset:3072
	v_mfma_f32_16x16x4_f32 v[240:243], v92, v212, v[240:243]
	ds_read_b32 v38, v239 offset:2048
	ds_read_b32 v39, v239 offset:2304
	ds_read_b128 v[140:143], v225 offset:9984
	v_mfma_f32_16x16x4_f32 v[244:247], v93, v213, v[244:247]
	ds_read_b128 v[144:147], v225 offset:11008
	ds_read_b128 v[148:151], v225 offset:12032
	ds_read_b128 v[152:155], v225 offset:13056
	v_mfma_f32_16x16x4_f32 v[240:243], v94, v214, v[240:243]
	ds_read_b32 v156, v227 offset:9988
	ds_read_b32 v157, v227 offset:10060
	v_mfma_f32_16x16x4_f32 v[244:247], v95, v215, v[244:247]
	ds_read_b64 v[158:159], v227 offset:9992
	ds_read_b64 v[160:161], v227 offset:10024
	v_mfma_f32_16x16x4_f32 v[240:243], v96, v216, v[240:243]
	ds_read_b32 v178, v229 offset:9988
	ds_read_b32 v179, v229 offset:10060
	v_mfma_f32_16x16x4_f32 v[244:247], v97, v217, v[244:247]
	ds_read_b64 v[180:181], v229 offset:9992
	ds_read_b64 v[182:183], v229 offset:10024
	v_mfma_f32_16x16x4_f32 v[240:243], v98, v218, v[240:243]
	ds_read_b64 v[162:163], v228 offset:9984
	ds_read_b64 v[164:165], v228 offset:10016
	v_mfma_f32_16x16x4_f32 v[244:247], v99, v219, v[244:247]
	ds_read_b64 v[166:167], v228 offset:10048
	ds_read_b64 v[168:169], v228 offset:10080
	v_mfma_f32_16x16x4_f32 v[240:243], v100, v220, v[240:243]
	ds_read_b64 v[170:171], v228 offset:9992
	ds_read_b64 v[172:173], v228 offset:10024
	v_mfma_f32_16x16x4_f32 v[244:247], v101, v221, v[244:247]
	ds_read_b64 v[174:175], v228 offset:10056
	ds_read_b64 v[176:177], v228 offset:10088
	v_mfma_f32_16x16x4_f32 v[240:243], v102, v222, v[240:243]
	v_mfma_f32_16x16x4_f32 v[244:247], v103, v223, v[244:247]
	s_setprio 3
	s_waitcnt lgkmcnt(15)
	v_mfma_f32_16x16x4_f32 v[208:211], v186, v36, v[208:211]
	s_nop 7
	v_pk_add_f32 v[240:241], v[240:241], v[244:245]
	v_pk_add_f32 v[242:243], v[242:243], v[246:247]
	v_fmac_f32_e32 v241, v104, v240
	v_mfma_f32_16x16x4_f32 v[212:215], v190, v36, v[212:215]
	v_pk_fma_f32 v[242:243], v[106:107], v[240:241], v[242:243] op_sel:[0,0,0] op_sel_hi:[1,0,1]
	v_pk_fma_f32 v[242:243], v[108:109], v[240:241], v[242:243] op_sel:[0,1,0] op_sel_hi:[1,1,1]
	v_fmac_f32_e32 v243, v105, v242
	v_mfma_f32_16x16x4_f32 v[216:219], v194, v36, v[216:219]
	ds_bpermute_b32 v204, v232, v240
	ds_bpermute_b32 v205, v232, v241
	ds_bpermute_b32 v206, v232, v242
	v_mfma_f32_16x16x4_f32 v[72:75], v132, v38, 0
	ds_bpermute_b32 v207, v232, v243
	s_waitcnt lgkmcnt(2)
	v_pk_fma_f32 v[240:241], v[110:111], v[204:205], v[240:241] op_sel:[0,0,0] op_sel_hi:[1,0,1]
	v_pk_fma_f32 v[240:241], v[112:113], v[204:205], v[240:241] op_sel:[0,1,0] op_sel_hi:[1,1,1]
	v_mfma_f32_16x16x4_f32 v[72:75], v133, v39, v[72:75]
	s_waitcnt lgkmcnt(0)
	v_pk_fma_f32 v[240:241], v[114:115], v[206:207], v[240:241] op_sel:[0,0,0] op_sel_hi:[1,0,1]
	v_pk_fma_f32 v[240:241], v[116:117], v[206:207], v[240:241] op_sel:[0,1,0] op_sel_hi:[1,1,1]
	v_pk_fma_f32 v[242:243], v[118:119], v[204:205], v[242:243] op_sel:[0,0,0] op_sel_hi:[1,0,1]
	v_mfma_f32_16x16x4_f32 v[220:223], v198, v36, v[220:223]
	v_pk_fma_f32 v[242:243], v[120:121], v[204:205], v[242:243] op_sel:[0,1,0] op_sel_hi:[1,1,1]
	v_pk_fma_f32 v[242:243], v[122:123], v[206:207], v[242:243] op_sel:[0,0,0] op_sel_hi:[1,0,1]
	v_pk_fma_f32 v[242:243], v[124:125], v[206:207], v[242:243] op_sel:[0,1,0] op_sel_hi:[1,1,1]
	v_mfma_f32_16x16x4_f32 v[208:211], v187, v37, v[208:211]
	v_fmac_f32_e32 v241, v126, v240
	v_pk_fma_f32 v[242:243], v[128:129], v[240:241], v[242:243] op_sel:[0,0,0] op_sel_hi:[1,0,1]
	v_pk_fma_f32 v[242:243], v[130:131], v[240:241], v[242:243] op_sel:[0,1,0] op_sel_hi:[1,1,1]
	v_mfma_f32_16x16x4_f32 v[212:215], v191, v37, v[212:215]
	v_fmac_f32_e32 v243, v127, v242
	v_mov_b32_e32 v252, v240
	v_mov_b32_e32 v253, v241
	v_mfma_f32_16x16x4_f32 v[216:219], v195, v37, v[216:219]
	v_mov_b32_e32 v254, v242
	v_mov_b32_e32 v255, v243
	s_nop 0
	v_permlane32_swap_b32_e32 v252, v254
	v_mfma_f32_16x16x4_f32 v[220:223], v199, v37, v[220:223]
	v_permlane32_swap_b32_e32 v253, v255
	s_setprio 0
	v_mfma_f32_16x16x4_f32 v[208:211], v184, v252, v[208:211]
	ds_read_b128 v[88:91], v226
	v_mfma_f32_16x16x4_f32 v[212:215], v188, v252, v[212:215]
	ds_read_b128 v[92:95], v226 offset:64
	v_mfma_f32_16x16x4_f32 v[216:219], v192, v252, v[216:219]
	ds_read_b128 v[96:99], v226 offset:128
	v_mfma_f32_16x16x4_f32 v[220:223], v196, v252, v[220:223]
	ds_read_b128 v[100:103], v226 offset:192
	v_mfma_f32_16x16x4_f32 v[208:211], v185, v253, v[208:211]
	v_mfma_f32_16x16x4_f32 v[212:215], v189, v253, v[212:215]
	v_mfma_f32_16x16x4_f32 v[216:219], v193, v253, v[216:219]
	v_mfma_f32_16x16x4_f32 v[220:223], v197, v253, v[220:223]
	v_mfma_f32_16x16x4_f32 v[248:251], v82, v252, v[240:243]
	v_mfma_f32_16x16x4_f32 v[248:251], v83, v253, v[248:251]
	s_waitcnt lgkmcnt(3)
	v_pk_mul_f32 v[208:209], v[208:209], v[88:89]
	v_pk_mul_f32 v[210:211], v[210:211], v[90:91]
	s_nop 0
	v_mfma_f32_16x16x4_f32 v[72:75], v140, v208, v[72:75]
	s_waitcnt lgkmcnt(2)
	v_pk_mul_f32 v[212:213], v[212:213], v[92:93]
	v_mfma_f32_16x16x4_f32 v[244:247], v141, v209, 0
	v_pk_mul_f32 v[214:215], v[214:215], v[94:95]
	v_mfma_f32_16x16x4_f32 v[72:75], v142, v210, v[72:75]
	s_waitcnt lgkmcnt(1)
	v_pk_mul_f32 v[216:217], v[216:217], v[96:97]
	v_mfma_f32_16x16x4_f32 v[244:247], v143, v211, v[244:247]
	v_pk_mul_f32 v[218:219], v[218:219], v[98:99]
	v_mfma_f32_16x16x4_f32 v[72:75], v144, v212, v[72:75]
	s_waitcnt lgkmcnt(0)
	v_pk_mul_f32 v[220:221], v[220:221], v[100:101]
	v_mfma_f32_16x16x4_f32 v[244:247], v145, v213, v[244:247]
	v_pk_mul_f32 v[222:223], v[222:223], v[102:103]
	v_mfma_f32_16x16x4_f32 v[72:75], v146, v214, v[72:75]
	s_mov_b64 exec, s[98:99]
	ds_write_b32 v231, v248
	ds_write_b32 v231, v249 offset:256
	ds_write_b32 v231, v250 offset:512
	ds_write_b32 v231, v251 offset:768
	s_mov_b64 exec, -1
	ds_read_b64 v[186:187], v34 offset:9984
	ds_read_b64 v[190:191], v34 offset:11008
	v_mfma_f32_16x16x4_f32 v[244:247], v147, v215, v[244:247]
	ds_read_b64 v[194:195], v34 offset:12032
	ds_read_b64 v[198:199], v34 offset:13056
	v_mfma_f32_16x16x4_f32 v[72:75], v148, v216, v[72:75]
	ds_read_b64 v[184:185], v236 offset:9984
	ds_read_b64 v[188:189], v236 offset:11008
	ds_read_b64 v[80:81], v32
	v_mfma_f32_16x16x4_f32 v[244:247], v149, v217, v[244:247]
	ds_read_b64 v[82:83], v33
	ds_read_b32 v36, v239 offset:4096
	ds_read_b64 v[192:193], v236 offset:12032
	v_mfma_f32_16x16x4_f32 v[72:75], v150, v218, v[72:75]
	ds_read_b64 v[196:197], v236 offset:13056
	ds_read_b32 v37, v239 offset:4352
	ds_read_b128 v[88:91], v26
	v_mfma_f32_16x16x4_f32 v[244:247], v151, v219, v[244:247]
	ds_read_b128 v[92:95], v26 offset:1024
	ds_read_b128 v[96:99], v26 offset:2048
	ds_read_b128 v[100:103], v26 offset:3072
	v_mfma_f32_16x16x4_f32 v[72:75], v152, v220, v[72:75]
	ds_read_b32 v104, v29 offset:4
	ds_read_b32 v105, v29 offset:76
	ds_read_b64 v[106:107], v29 offset:8
	v_mfma_f32_16x16x4_f32 v[244:247], v153, v221, v[244:247]
	ds_read_b64 v[108:109], v29 offset:40
	ds_read_b32 v126, v31 offset:4
	ds_read_b32 v127, v31 offset:76
	v_mfma_f32_16x16x4_f32 v[72:75], v154, v222, v[72:75]
	ds_read_b64 v[128:129], v31 offset:8
	ds_read_b64 v[130:131], v31 offset:40
	ds_read_b64 v[110:111], v30
	v_mfma_f32_16x16x4_f32 v[244:247], v155, v223, v[244:247]
	ds_read_b64 v[112:113], v30 offset:32
	ds_read_b64 v[114:115], v30 offset:64
	ds_read_b64 v[116:117], v30 offset:96
	ds_read_b64 v[118:119], v30 offset:8
	ds_read_b64 v[120:121], v30 offset:40
	ds_read_b64 v[122:123], v30 offset:72
	ds_read_b64 v[124:125], v30 offset:104
	s_setprio 3
	s_waitcnt lgkmcnt(15)
	v_mfma_f32_16x16x4_f32 v[208:211], v186, v38, v[208:211]
	s_nop 0
	v_pk_add_f32 v[72:73], v[72:73], v[244:245]
	v_pk_add_f32 v[74:75], v[74:75], v[246:247]
	v_fmac_f32_e32 v73, v156, v72
	v_mfma_f32_16x16x4_f32 v[212:215], v190, v38, v[212:215]
	v_pk_fma_f32 v[74:75], v[158:159], v[72:73], v[74:75] op_sel:[0,0,0] op_sel_hi:[1,0,1]
	v_pk_fma_f32 v[74:75], v[160:161], v[72:73], v[74:75] op_sel:[0,1,0] op_sel_hi:[1,1,1]
	v_fmac_f32_e32 v75, v157, v74
	v_mfma_f32_16x16x4_f32 v[216:219], v194, v38, v[216:219]
	ds_bpermute_b32 v204, v232, v72
	ds_bpermute_b32 v205, v232, v73
	ds_bpermute_b32 v206, v232, v74
	v_mfma_f32_16x16x4_f32 v[240:243], v80, v36, 0
	ds_bpermute_b32 v207, v232, v75
	s_waitcnt lgkmcnt(2)
	v_pk_fma_f32 v[72:73], v[162:163], v[204:205], v[72:73] op_sel:[0,0,0] op_sel_hi:[1,0,1]
	v_pk_fma_f32 v[72:73], v[164:165], v[204:205], v[72:73] op_sel:[0,1,0] op_sel_hi:[1,1,1]
	v_mfma_f32_16x16x4_f32 v[240:243], v81, v37, v[240:243]
	s_waitcnt lgkmcnt(0)
	v_pk_fma_f32 v[72:73], v[166:167], v[206:207], v[72:73] op_sel:[0,0,0] op_sel_hi:[1,0,1]
	v_pk_fma_f32 v[72:73], v[168:169], v[206:207], v[72:73] op_sel:[0,1,0] op_sel_hi:[1,1,1]
	v_pk_fma_f32 v[74:75], v[170:171], v[204:205], v[74:75] op_sel:[0,0,0] op_sel_hi:[1,0,1]
	v_mfma_f32_16x16x4_f32 v[220:223], v198, v38, v[220:223]
	v_pk_fma_f32 v[74:75], v[172:173], v[204:205], v[74:75] op_sel:[0,1,0] op_sel_hi:[1,1,1]
	v_pk_fma_f32 v[74:75], v[174:175], v[206:207], v[74:75] op_sel:[0,0,0] op_sel_hi:[1,0,1]
	v_pk_fma_f32 v[74:75], v[176:177], v[206:207], v[74:75] op_sel:[0,1,0] op_sel_hi:[1,1,1]
	v_mfma_f32_16x16x4_f32 v[208:211], v187, v39, v[208:211]
	v_fmac_f32_e32 v73, v178, v72
	v_pk_fma_f32 v[74:75], v[180:181], v[72:73], v[74:75] op_sel:[0,0,0] op_sel_hi:[1,0,1]
	v_pk_fma_f32 v[74:75], v[182:183], v[72:73], v[74:75] op_sel:[0,1,0] op_sel_hi:[1,1,1]
	v_mfma_f32_16x16x4_f32 v[212:215], v191, v39, v[212:215]
	v_fmac_f32_e32 v75, v179, v74
	v_mov_b32_e32 v252, v72
	v_mov_b32_e32 v253, v73
	v_mfma_f32_16x16x4_f32 v[216:219], v195, v39, v[216:219]
	v_mov_b32_e32 v254, v74
	v_mov_b32_e32 v255, v75
	s_nop 0
	v_permlane32_swap_b32_e32 v252, v254
	v_mfma_f32_16x16x4_f32 v[220:223], v199, v39, v[220:223]
	v_permlane32_swap_b32_e32 v253, v255
	s_setprio 0
	v_mfma_f32_16x16x4_f32 v[208:211], v184, v252, v[208:211]
	ds_read_b128 v[140:143], v226 offset:9984
	v_mfma_f32_16x16x4_f32 v[212:215], v188, v252, v[212:215]
	ds_read_b128 v[144:147], v226 offset:10048
	v_mfma_f32_16x16x4_f32 v[216:219], v192, v252, v[216:219]
	ds_read_b128 v[148:151], v226 offset:10112
	v_mfma_f32_16x16x4_f32 v[220:223], v196, v252, v[220:223]
	ds_read_b128 v[152:155], v226 offset:10176
	v_mfma_f32_16x16x4_f32 v[208:211], v185, v253, v[208:211]
	v_mfma_f32_16x16x4_f32 v[212:215], v189, v253, v[212:215]
	v_mfma_f32_16x16x4_f32 v[216:219], v193, v253, v[216:219]
	v_mfma_f32_16x16x4_f32 v[220:223], v197, v253, v[220:223]
	v_mfma_f32_16x16x4_f32 v[248:251], v134, v252, v[72:75]
	v_mfma_f32_16x16x4_f32 v[248:251], v135, v253, v[248:251]
	s_waitcnt lgkmcnt(3)
	v_pk_mul_f32 v[208:209], v[208:209], v[140:141]
	v_pk_mul_f32 v[210:211], v[210:211], v[142:143]
	s_nop 0
	v_mfma_f32_16x16x4_f32 v[240:243], v88, v208, v[240:243]
	s_waitcnt lgkmcnt(2)
	v_pk_mul_f32 v[212:213], v[212:213], v[144:145]
	v_mfma_f32_16x16x4_f32 v[244:247], v89, v209, 0
	v_pk_mul_f32 v[214:215], v[214:215], v[146:147]
	v_mfma_f32_16x16x4_f32 v[240:243], v90, v210, v[240:243]
	s_waitcnt lgkmcnt(1)
	v_pk_mul_f32 v[216:217], v[216:217], v[148:149]
	v_mfma_f32_16x16x4_f32 v[244:247], v91, v211, v[244:247]
	v_pk_mul_f32 v[218:219], v[218:219], v[150:151]
	v_mfma_f32_16x16x4_f32 v[240:243], v92, v212, v[240:243]
	s_waitcnt lgkmcnt(0)
	v_pk_mul_f32 v[220:221], v[220:221], v[152:153]
	v_mfma_f32_16x16x4_f32 v[244:247], v93, v213, v[244:247]
	v_pk_mul_f32 v[222:223], v[222:223], v[154:155]
	v_mfma_f32_16x16x4_f32 v[240:243], v94, v214, v[240:243]
	s_mov_b64 exec, s[98:99]
	ds_write_b32 v231, v248 offset:2048
	ds_write_b32 v231, v249 offset:2304
	ds_write_b32 v231, v250 offset:2560
	ds_write_b32 v231, v251 offset:2816
	s_mov_b64 exec, -1
	ds_read_b64 v[186:187], v35
	ds_read_b64 v[190:191], v35 offset:1024
	v_mfma_f32_16x16x4_f32 v[244:247], v95, v215, v[244:247]
	ds_read_b64 v[194:195], v35 offset:2048
	ds_read_b64 v[198:199], v35 offset:3072
	v_mfma_f32_16x16x4_f32 v[240:243], v96, v216, v[240:243]
	ds_read_b64 v[184:185], v27
	ds_read_b64 v[188:189], v27 offset:1024
	ds_read_b64 v[132:133], v32 offset:9984
	v_mfma_f32_16x16x4_f32 v[244:247], v97, v217, v[244:247]
	ds_read_b64 v[134:135], v33 offset:9984
	ds_read_b32 v38, v239 offset:6144
	ds_read_b64 v[192:193], v27 offset:2048
	v_mfma_f32_16x16x4_f32 v[240:243], v98, v218, v[240:243]
	ds_read_b64 v[196:197], v27 offset:3072
	ds_read_b32 v39, v239 offset:6400
	ds_read_b128 v[140:143], v26 offset:9984
	v_mfma_f32_16x16x4_f32 v[244:247], v99, v219, v[244:247]
	ds_read_b128 v[144:147], v26 offset:11008
	ds_read_b128 v[148:151], v26 offset:12032
	ds_read_b128 v[152:155], v26 offset:13056
	v_mfma_f32_16x16x4_f32 v[240:243], v100, v220, v[240:243]
	ds_read_b32 v156, v29 offset:9988
	ds_read_b32 v157, v29 offset:10060
	ds_read_b64 v[158:159], v29 offset:9992
	v_mfma_f32_16x16x4_f32 v[244:247], v101, v221, v[244:247]
	ds_read_b64 v[160:161], v29 offset:10024
	ds_read_b32 v178, v31 offset:9988
	ds_read_b32 v179, v31 offset:10060
	v_mfma_f32_16x16x4_f32 v[240:243], v102, v222, v[240:243]
	ds_read_b64 v[180:181], v31 offset:9992
	ds_read_b64 v[182:183], v31 offset:10024
	ds_read_b64 v[162:163], v30 offset:9984
	v_mfma_f32_16x16x4_f32 v[244:247], v103, v223, v[244:247]
	ds_read_b64 v[164:165], v30 offset:10016
	ds_read_b64 v[166:167], v30 offset:10048
	ds_read_b64 v[168:169], v30 offset:10080
	ds_read_b64 v[170:171], v30 offset:9992
	ds_read_b64 v[172:173], v30 offset:10024
	ds_read_b64 v[174:175], v30 offset:10056
	ds_read_b64 v[176:177], v30 offset:10088
	s_setprio 3
	s_waitcnt lgkmcnt(15)
	v_mfma_f32_16x16x4_f32 v[208:211], v186, v36, v[208:211]
	s_nop 0
	v_pk_add_f32 v[240:241], v[240:241], v[244:245]
	v_pk_add_f32 v[242:243], v[242:243], v[246:247]
	v_fmac_f32_e32 v241, v104, v240
	v_mfma_f32_16x16x4_f32 v[212:215], v190, v36, v[212:215]
	v_pk_fma_f32 v[242:243], v[106:107], v[240:241], v[242:243] op_sel:[0,0,0] op_sel_hi:[1,0,1]
	v_pk_fma_f32 v[242:243], v[108:109], v[240:241], v[242:243] op_sel:[0,1,0] op_sel_hi:[1,1,1]
	v_fmac_f32_e32 v243, v105, v242
	v_mfma_f32_16x16x4_f32 v[216:219], v194, v36, v[216:219]
	ds_bpermute_b32 v204, v232, v240
	ds_bpermute_b32 v205, v232, v241
	ds_bpermute_b32 v206, v232, v242
	v_mfma_f32_16x16x4_f32 v[72:75], v132, v38, 0
	ds_bpermute_b32 v207, v232, v243
	s_waitcnt lgkmcnt(2)
	v_pk_fma_f32 v[240:241], v[110:111], v[204:205], v[240:241] op_sel:[0,0,0] op_sel_hi:[1,0,1]
	v_pk_fma_f32 v[240:241], v[112:113], v[204:205], v[240:241] op_sel:[0,1,0] op_sel_hi:[1,1,1]
	v_mfma_f32_16x16x4_f32 v[72:75], v133, v39, v[72:75]
	s_waitcnt lgkmcnt(0)
	v_pk_fma_f32 v[240:241], v[114:115], v[206:207], v[240:241] op_sel:[0,0,0] op_sel_hi:[1,0,1]
	v_pk_fma_f32 v[240:241], v[116:117], v[206:207], v[240:241] op_sel:[0,1,0] op_sel_hi:[1,1,1]
	v_pk_fma_f32 v[242:243], v[118:119], v[204:205], v[242:243] op_sel:[0,0,0] op_sel_hi:[1,0,1]
	v_mfma_f32_16x16x4_f32 v[220:223], v198, v36, v[220:223]
	v_pk_fma_f32 v[242:243], v[120:121], v[204:205], v[242:243] op_sel:[0,1,0] op_sel_hi:[1,1,1]
	v_pk_fma_f32 v[242:243], v[122:123], v[206:207], v[242:243] op_sel:[0,0,0] op_sel_hi:[1,0,1]
	v_pk_fma_f32 v[242:243], v[124:125], v[206:207], v[242:243] op_sel:[0,1,0] op_sel_hi:[1,1,1]
	v_mfma_f32_16x16x4_f32 v[208:211], v187, v37, v[208:211]
	v_fmac_f32_e32 v241, v126, v240
	v_pk_fma_f32 v[242:243], v[128:129], v[240:241], v[242:243] op_sel:[0,0,0] op_sel_hi:[1,0,1]
	v_pk_fma_f32 v[242:243], v[130:131], v[240:241], v[242:243] op_sel:[0,1,0] op_sel_hi:[1,1,1]
	v_mfma_f32_16x16x4_f32 v[212:215], v191, v37, v[212:215]
	v_fmac_f32_e32 v243, v127, v242
	v_mov_b32_e32 v252, v240
	v_mov_b32_e32 v253, v241
	v_mfma_f32_16x16x4_f32 v[216:219], v195, v37, v[216:219]
	v_mov_b32_e32 v254, v242
	v_mov_b32_e32 v255, v243
	s_nop 0
	v_permlane32_swap_b32_e32 v252, v254
	v_mfma_f32_16x16x4_f32 v[220:223], v199, v37, v[220:223]
	v_permlane32_swap_b32_e32 v253, v255
	s_setprio 0
	v_mfma_f32_16x16x4_f32 v[208:211], v184, v252, v[208:211]
	ds_read_b128 v[88:91], v28
	v_mfma_f32_16x16x4_f32 v[212:215], v188, v252, v[212:215]
	ds_read_b128 v[92:95], v28 offset:64
	v_mfma_f32_16x16x4_f32 v[216:219], v192, v252, v[216:219]
	ds_read_b128 v[96:99], v28 offset:128
	v_mfma_f32_16x16x4_f32 v[220:223], v196, v252, v[220:223]
	ds_read_b128 v[100:103], v28 offset:192
	v_mfma_f32_16x16x4_f32 v[208:211], v185, v253, v[208:211]
	v_mfma_f32_16x16x4_f32 v[212:215], v189, v253, v[212:215]
	v_mfma_f32_16x16x4_f32 v[216:219], v193, v253, v[216:219]
	v_mfma_f32_16x16x4_f32 v[220:223], v197, v253, v[220:223]
	v_mfma_f32_16x16x4_f32 v[248:251], v82, v252, v[240:243]
	v_mfma_f32_16x16x4_f32 v[248:251], v83, v253, v[248:251]
	s_waitcnt lgkmcnt(3)
	v_pk_mul_f32 v[208:209], v[208:209], v[88:89]
	v_pk_mul_f32 v[210:211], v[210:211], v[90:91]
	s_nop 0
	v_mfma_f32_16x16x4_f32 v[72:75], v140, v208, v[72:75]
	s_waitcnt lgkmcnt(2)
	v_pk_mul_f32 v[212:213], v[212:213], v[92:93]
	v_mfma_f32_16x16x4_f32 v[244:247], v141, v209, 0
	v_pk_mul_f32 v[214:215], v[214:215], v[94:95]
	v_mfma_f32_16x16x4_f32 v[72:75], v142, v210, v[72:75]
	s_waitcnt lgkmcnt(1)
	v_pk_mul_f32 v[216:217], v[216:217], v[96:97]
	v_mfma_f32_16x16x4_f32 v[244:247], v143, v211, v[244:247]
	v_pk_mul_f32 v[218:219], v[218:219], v[98:99]
	v_mfma_f32_16x16x4_f32 v[72:75], v144, v212, v[72:75]
	s_waitcnt lgkmcnt(0)
	v_pk_mul_f32 v[220:221], v[220:221], v[100:101]
	v_mfma_f32_16x16x4_f32 v[244:247], v145, v213, v[244:247]
	v_pk_mul_f32 v[222:223], v[222:223], v[102:103]
	v_mfma_f32_16x16x4_f32 v[72:75], v146, v214, v[72:75]
	s_mov_b64 exec, s[98:99]
	ds_write_b32 v231, v248 offset:4096
	ds_write_b32 v231, v249 offset:4352
	ds_write_b32 v231, v250 offset:4608
	ds_write_b32 v231, v251 offset:4864
	s_mov_b64 exec, -1
	ds_read_b64 v[186:187], v35 offset:9984
	ds_read_b64 v[190:191], v35 offset:11008
	v_mfma_f32_16x16x4_f32 v[244:247], v147, v215, v[244:247]
	ds_read_b64 v[194:195], v35 offset:12032
	ds_read_b64 v[198:199], v35 offset:13056
	v_mfma_f32_16x16x4_f32 v[72:75], v148, v216, v[72:75]
	ds_read_b64 v[184:185], v27 offset:9984
	ds_read_b64 v[188:189], v27 offset:11008
	v_mfma_f32_16x16x4_f32 v[244:247], v149, v217, v[244:247]
	ds_read_b64 v[192:193], v27 offset:12032
	ds_read_b64 v[196:197], v27 offset:13056
	v_mfma_f32_16x16x4_f32 v[72:75], v150, v218, v[72:75]
	v_mfma_f32_16x16x4_f32 v[244:247], v151, v219, v[244:247]
	v_mfma_f32_16x16x4_f32 v[72:75], v152, v220, v[72:75]
	v_mfma_f32_16x16x4_f32 v[244:247], v153, v221, v[244:247]
	v_mfma_f32_16x16x4_f32 v[72:75], v154, v222, v[72:75]
	v_mfma_f32_16x16x4_f32 v[244:247], v155, v223, v[244:247]
	s_setprio 3
	s_waitcnt lgkmcnt(7)
	v_mfma_f32_16x16x4_f32 v[208:211], v186, v38, v[208:211]
	s_nop 7
	v_pk_add_f32 v[72:73], v[72:73], v[244:245]
	v_pk_add_f32 v[74:75], v[74:75], v[246:247]
	v_fmac_f32_e32 v73, v156, v72
	s_waitcnt lgkmcnt(6)
	v_mfma_f32_16x16x4_f32 v[212:215], v190, v38, v[212:215]
	v_pk_fma_f32 v[74:75], v[158:159], v[72:73], v[74:75] op_sel:[0,0,0] op_sel_hi:[1,0,1]
	v_pk_fma_f32 v[74:75], v[160:161], v[72:73], v[74:75] op_sel:[0,1,0] op_sel_hi:[1,1,1]
	v_fmac_f32_e32 v75, v157, v74
	s_waitcnt lgkmcnt(5)
	v_mfma_f32_16x16x4_f32 v[216:219], v194, v38, v[216:219]
	ds_bpermute_b32 v204, v232, v72
	ds_bpermute_b32 v205, v232, v73
	ds_bpermute_b32 v206, v232, v74
	s_waitcnt lgkmcnt(7)
	v_mfma_f32_16x16x4_f32 v[220:223], v198, v38, v[220:223]
	ds_bpermute_b32 v207, v232, v75
	s_waitcnt lgkmcnt(2)
	v_pk_fma_f32 v[72:73], v[162:163], v[204:205], v[72:73] op_sel:[0,0,0] op_sel_hi:[1,0,1]
	v_pk_fma_f32 v[72:73], v[164:165], v[204:205], v[72:73] op_sel:[0,1,0] op_sel_hi:[1,1,1]
	v_mfma_f32_16x16x4_f32 v[208:211], v187, v39, v[208:211]
	s_waitcnt lgkmcnt(0)
	v_pk_fma_f32 v[72:73], v[166:167], v[206:207], v[72:73] op_sel:[0,0,0] op_sel_hi:[1,0,1]
	v_pk_fma_f32 v[72:73], v[168:169], v[206:207], v[72:73] op_sel:[0,1,0] op_sel_hi:[1,1,1]
	v_pk_fma_f32 v[74:75], v[170:171], v[204:205], v[74:75] op_sel:[0,0,0] op_sel_hi:[1,0,1]
	v_mfma_f32_16x16x4_f32 v[212:215], v191, v39, v[212:215]
	v_pk_fma_f32 v[74:75], v[172:173], v[204:205], v[74:75] op_sel:[0,1,0] op_sel_hi:[1,1,1]
	v_pk_fma_f32 v[74:75], v[174:175], v[206:207], v[74:75] op_sel:[0,0,0] op_sel_hi:[1,0,1]
	v_pk_fma_f32 v[74:75], v[176:177], v[206:207], v[74:75] op_sel:[0,1,0] op_sel_hi:[1,1,1]
	v_mfma_f32_16x16x4_f32 v[216:219], v195, v39, v[216:219]
	v_fmac_f32_e32 v73, v178, v72
	v_pk_fma_f32 v[74:75], v[180:181], v[72:73], v[74:75] op_sel:[0,0,0] op_sel_hi:[1,0,1]
	v_pk_fma_f32 v[74:75], v[182:183], v[72:73], v[74:75] op_sel:[0,1,0] op_sel_hi:[1,1,1]
	v_mfma_f32_16x16x4_f32 v[220:223], v199, v39, v[220:223]
	v_fmac_f32_e32 v75, v179, v74
	v_mov_b32_e32 v252, v72
	v_mov_b32_e32 v253, v73
	v_mov_b32_e32 v254, v74
	v_mov_b32_e32 v255, v75
	s_nop 0
	v_permlane32_swap_b32_e32 v252, v254
	v_permlane32_swap_b32_e32 v253, v255
	s_setprio 0
	v_mfma_f32_16x16x4_f32 v[208:211], v184, v252, v[208:211]
	ds_read_b128 v[140:143], v28 offset:9984
	v_mfma_f32_16x16x4_f32 v[212:215], v188, v252, v[212:215]
	ds_read_b128 v[144:147], v28 offset:10048
	v_mfma_f32_16x16x4_f32 v[216:219], v192, v252, v[216:219]
	ds_read_b128 v[148:151], v28 offset:10112
	v_mfma_f32_16x16x4_f32 v[220:223], v196, v252, v[220:223]
	ds_read_b128 v[152:155], v28 offset:10176
	v_mfma_f32_16x16x4_f32 v[208:211], v185, v253, v[208:211]
	v_mfma_f32_16x16x4_f32 v[212:215], v189, v253, v[212:215]
	v_mfma_f32_16x16x4_f32 v[216:219], v193, v253, v[216:219]
	v_mfma_f32_16x16x4_f32 v[220:223], v197, v253, v[220:223]
	v_mfma_f32_16x16x4_f32 v[248:251], v134, v252, v[72:75]
	v_mfma_f32_16x16x4_f32 v[248:251], v135, v253, v[248:251]
	s_waitcnt lgkmcnt(3)
	v_pk_mul_f32 v[208:209], v[208:209], v[140:141]
	v_pk_mul_f32 v[210:211], v[210:211], v[142:143]
	s_waitcnt lgkmcnt(2)
	v_pk_mul_f32 v[212:213], v[212:213], v[144:145]
	v_pk_mul_f32 v[214:215], v[214:215], v[146:147]
	s_waitcnt lgkmcnt(1)
	v_pk_mul_f32 v[216:217], v[216:217], v[148:149]
	v_pk_mul_f32 v[218:219], v[218:219], v[150:151]
	s_waitcnt lgkmcnt(0)
	v_pk_mul_f32 v[220:221], v[220:221], v[152:153]
	v_pk_mul_f32 v[222:223], v[222:223], v[154:155]
	s_mov_b64 exec, s[98:99]
	s_nop 0
	ds_write_b32 v231, v248 offset:6144
	ds_write_b32 v231, v249 offset:6400
	ds_write_b32 v231, v250 offset:6656
	ds_write_b32 v231, v251 offset:6912
	s_mov_b64 exec, -1
	s_branch .LBB0_655

.Lmy_ck_drE_h:
	s_waitcnt lgkmcnt(0)
	s_bfe_u32 s96, s62, 0x20006
	s_and_b32 s97, s96, 1
	s_mul_i32 s97, s97, 0x2700
	s_mov_b32 s101, 0x1c000
	s_mov_b32 s100, 0x6100
	s_bitcmp0_b32 s65, 0
	s_cselect_b32 s101, 0xe000, s101
	s_cselect_b32 s100, 0x4e00, s100
	s_cmp_gt_u32 s96, 1
	s_cselect_b32 s100, s100, 0
	s_add_i32 s97, s97, s101
	s_add_i32 s97, s97, s100
	s_mov_b32 s96, s97
	v_and_b32_e32 v72, 3, v233
	v_lshrrev_b32_e32 v73, 2, v233
	v_lshlrev_b32_e32 v72, 2, v72
	v_lshl_add_u32 v72, v73, 8, v72
	v_lshl_add_u32 v72, v234, 6, v72
	s_add_i32 s97, s96, 0x1000
	v_add_u32_e32 v78, s97, v72
	v_xor_b32_e32 v79, v224, v234
	v_lshl_add_u32 v79, v79, 4, s96
	ds_read_b128 v[96:99], v79
	ds_read_b128 v[100:103], v79 offset:1024
	ds_read_b128 v[104:107], v79 offset:2048
	ds_read_b128 v[108:111], v79 offset:3072
	ds_read_b32 v80, v78
	ds_read_b32 v81, v78 offset:16
	ds_read_b32 v82, v78 offset:32
	ds_read_b32 v83, v78 offset:48
	ds_read_b32 v84, v78 offset:1024
	ds_read_b32 v85, v78 offset:1040
	ds_read_b32 v86, v78 offset:1056
	ds_read_b32 v87, v78 offset:1072
	ds_read_b32 v88, v78 offset:2048
	ds_read_b32 v89, v78 offset:2064
	ds_read_b32 v90, v78 offset:2080
	ds_read_b32 v91, v78 offset:2096
	ds_read_b32 v92, v78 offset:3072
	ds_read_b32 v93, v78 offset:3088
	ds_read_b32 v94, v78 offset:3104
	ds_read_b32 v95, v78 offset:3120
	v_lshl_add_u32 v74, v224, 2, s96
	ds_write_b32 v74, v235 offset:9728
	v_add_u32_e32 v75, -1, v233
	v_mov_b32_e32 v76, -1
	v_cndmask_b32_e64 v75, v76, v75, s[98:99]
	v_cmp_lt_u32_e64 s[100:101], 7, v233
	v_add_u32_e32 v76, -8, v233
	v_and_b32_e32 v77, 1, v234
	v_cndmask_b32_e64 v75, v75, v76, s[100:101]
	v_lshlrev_b32_e32 v77, 2, v77
	v_sub_u32_e32 v76, v75, v77
	v_lshlrev_b32_e32 v77, 2, v234
	v_sub_u32_e32 v77, v233, v77
	v_add_u32_e32 v77, -1, v77
	s_waitcnt lgkmcnt(15)
	v_mfma_f32_16x16x4_f32 v[244:247], v80, v96, 0
	v_mfma_f32_16x16x4_f32 v[240:243], v81, v97, 0
	s_waitcnt lgkmcnt(14)
	v_mfma_f32_16x16x4_f32 v[244:247], v82, v98, v[244:247]
	s_waitcnt lgkmcnt(13)
	v_mfma_f32_16x16x4_f32 v[240:243], v83, v99, v[240:243]
	s_waitcnt lgkmcnt(12)
	v_mfma_f32_16x16x4_f32 v[244:247], v84, v100, v[244:247]
	s_waitcnt lgkmcnt(11)
	v_mfma_f32_16x16x4_f32 v[240:243], v85, v101, v[240:243]
	s_waitcnt lgkmcnt(10)
	v_mfma_f32_16x16x4_f32 v[244:247], v86, v102, v[244:247]
	s_waitcnt lgkmcnt(9)
	v_mfma_f32_16x16x4_f32 v[240:243], v87, v103, v[240:243]
	s_waitcnt lgkmcnt(8)
	v_mfma_f32_16x16x4_f32 v[244:247], v88, v104, v[244:247]
	s_waitcnt lgkmcnt(7)
	v_mfma_f32_16x16x4_f32 v[240:243], v89, v105, v[240:243]
	s_waitcnt lgkmcnt(6)
	v_mfma_f32_16x16x4_f32 v[244:247], v90, v106, v[244:247]
	s_waitcnt lgkmcnt(5)
	v_mfma_f32_16x16x4_f32 v[240:243], v91, v107, v[240:243]
	s_waitcnt lgkmcnt(4)
	v_mfma_f32_16x16x4_f32 v[244:247], v92, v108, v[244:247]
	s_waitcnt lgkmcnt(3)
	v_mfma_f32_16x16x4_f32 v[240:243], v93, v109, v[240:243]
	s_waitcnt lgkmcnt(2)
	v_mfma_f32_16x16x4_f32 v[244:247], v94, v110, v[244:247]
	s_waitcnt lgkmcnt(1)
	v_mfma_f32_16x16x4_f32 v[240:243], v95, v111, v[240:243]
	s_nop 9
	v_add_f32_e32 v244, v244, v240
	v_add_f32_e32 v245, v245, v241
	v_add_f32_e32 v246, v246, v242
	v_add_f32_e32 v247, v247, v243
	v_cmp_le_i32_e64 s[96:97], 0, v76
	v_cmp_le_i32_e64 s[100:101], 1, v76
	s_nop 0
	v_cndmask_b32_e64 v128, 0, v244, s[96:97]
	v_cndmask_b32_e64 v129, 0, v245, s[100:101]
	v_cmp_le_i32_e64 s[96:97], 2, v76
	v_cmp_le_i32_e64 s[100:101], 3, v76
	s_nop 0
	v_cndmask_b32_e64 v130, 0, v246, s[96:97]
	v_cndmask_b32_e64 v131, 0, v247, s[100:101]
	s_bfe_u32 s96, s62, 0x20006
	s_and_b32 s97, s96, 1
	s_mul_i32 s97, s97, 0x2700
	s_mov_b32 s101, 0x1c000
	s_mov_b32 s100, 0x6100
	s_bitcmp0_b32 s65, 0
	s_cselect_b32 s101, 0xe000, s101
	s_cselect_b32 s100, 0x4e00, s100
	s_cmp_gt_u32 s96, 1
	s_cselect_b32 s100, s100, 0
	s_add_i32 s97, s97, s101
	s_add_i32 s97, s97, s100
	v_xor_b32_e32 v74, v224, v234
	v_lshl_add_u32 v74, v74, 4, s97
	ds_write_b128 v74, v[128:131] offset:8448
	v_lshlrev_b32_e32 v75, 7, v234
	v_lshl_add_u32 v75, v233, 2, v75
	v_add_u32_e32 v75, s97, v75
	v_cmp_le_i32_e64 s[96:97], 0, v77
	v_cmp_le_i32_e64 s[100:101], 1, v77
	s_nop 0
	v_cndmask_b32_e64 v132, 0, v244, s[96:97]
	v_cndmask_b32_e64 v133, 0, v245, s[100:101]
	v_cmp_le_i32_e64 s[96:97], 2, v77
	v_cmp_le_i32_e64 s[100:101], 3, v77
	s_nop 0
	v_cndmask_b32_e64 v134, 0, v246, s[96:97]
	v_cndmask_b32_e64 v135, 0, v247, s[100:101]
	s_mov_b64 exec, 0x00ff00ff
	ds_write_b32 v75, v132 offset:9472
	ds_write_b32 v75, v133 offset:9504
	ds_write_b32 v75, v134 offset:9536
	ds_write_b32 v75, v135 offset:9568
	s_mov_b64 exec, -1
	s_setprio 0
	s_branch .LBB0_655
	s_nop 0
	s_nop 0
	s_nop 0
	s_nop 0
	s_nop 0
	s_nop 0
	s_nop 0
	s_nop 0
	s_nop 0
	s_nop 0
	s_nop 0
	s_nop 0
	s_nop 0
	s_nop 0
	s_nop 0
	s_nop 0
	s_nop 0
	s_nop 0
	s_nop 0
	s_nop 0
	s_nop 0
	s_nop 0
	s_nop 0
	s_nop 0
	s_nop 0
	s_nop 0
	s_nop 0
	s_nop 0
	s_nop 0
	s_nop 0
	s_nop 0
	s_nop 0
	s_nop 0
	s_nop 0
	s_nop 0
	s_nop 0
	s_nop 0
	s_nop 0
